# P5 final tile: the first half of the epilogue stores (issued inside the last MFMA segment) write-through, so the barrier's L2 write-back has half as much fresh dirty data
# speedup vs baseline: 1.0004x; 1.0004x over previous
mk_p5_chk:
	s_cmp_lg_u64 s[40:41], 0
	s_cbranch_scc1 .LBB0_716
	s_lshl_b32 s98, s74, 8
	s_add_i32 s98, s98, s48
	s_lshl_b32 s98, s98, 14
	s_lshl_b32 s99, s75, 8
	s_or_b32 s99, s99, s50
	s_lshl_b32 s99, s99, 1
	s_add_u32 s98, s98, s99
	s_add_u32 s98, s76, s98
	s_addc_u32 s99, s77, 0
	s_add_u32 s100, s98, 0x200000
	s_addc_u32 s101, s99, 0
	s_add_u32 s80, s46, 0x100
	s_addc_u32 s81, s47, 0
	s_cmp_eq_u32 s89, 28
	s_cselect_b32 s28, vcc_lo, s80
	s_cselect_b32 s29, s37, s81
	s_cselect_b32 s23, s21, s88
	s_cselect_b32 s22, s86, s87
	s_add_u32 s26, s28, 0x80
	s_addc_u32 s27, s29, 0
	s_add_u32 s66, s22, 0x80
	s_addc_u32 s67, s23, 0
	s_add_u32 s90, s46, 0x80080
	s_addc_u32 s91, s47, 0
	s_add_u32 s52, s28, 0x80000
	s_addc_u32 s53, s29, 0
	s_add_u32 s56, s22, 0x80000
	s_addc_u32 s57, s23, 0
	s_add_u32 s46, s22, 0x80080
	s_addc_u32 s47, s23, 0
	s_add_i32 s92, 0, 0x10000
	v_add_u32_e32 v133, s92, v129
	s_add_i32 s93, 0, 0x14000
	ds_read_b128 v[134:137], v133
	ds_read_b128 v[138:141], v133 offset:1024
	ds_read_b128 v[142:145], v133 offset:2048
	ds_read_b128 v[146:149], v133 offset:3072
	v_add_u32_e32 v133, s93, v129
	ds_read_b128 v[150:153], v133
	ds_read_b128 v[154:157], v133 offset:1024
	ds_read_b128 v[158:161], v133 offset:2048
	ds_read_b128 v[162:165], v133 offset:3072
	s_add_i32 m0, s0, 0xc000
	ds_read_b128 v[166:169], v131
	ds_read_b128 v[170:173], v131 offset:1024
	ds_read_b128 v[174:177], v131 offset:2048
	ds_read_b128 v[178:181], v131 offset:3072
	ds_read_b128 v[182:185], v131 offset:4096
	ds_read_b128 v[186:189], v131 offset:5120
	ds_read_b128 v[202:205], v131 offset:6144
	ds_read_b128 v[206:209], v131 offset:7168
	global_load_lds_dwordx4 v128, s[90:91]
	s_add_i32 m0, s0, 0xe000
	s_nop 0
	global_load_lds_dwordx4 v130, s[90:91]
	s_waitcnt vmcnt(8)
	s_waitcnt lgkmcnt(0)
	s_barrier
	s_setprio 1
	s_waitcnt lgkmcnt(0)
	v_mfma_f32_16x16x32_bf16 v[124:127], v[134:137], v[166:169], v[124:127]
	v_mfma_f32_16x16x32_bf16 v[120:123], v[142:145], v[166:169], v[120:123]
	v_mfma_f32_16x16x32_bf16 v[108:111], v[134:137], v[174:177], v[108:111]
	v_mfma_f32_16x16x32_bf16 v[104:107], v[142:145], v[174:177], v[104:107]
	v_mfma_f32_16x16x32_bf16 v[92:95], v[134:137], v[182:185], v[92:95]
	v_mfma_f32_16x16x32_bf16 v[88:91], v[142:145], v[182:185], v[88:91]
	v_mfma_f32_16x16x32_bf16 v[76:79], v[134:137], v[202:205], v[76:79]
	v_mfma_f32_16x16x32_bf16 v[72:75], v[142:145], v[202:205], v[72:75]
	v_mfma_f32_16x16x32_bf16 v[124:127], v[138:141], v[170:173], v[124:127]
	v_mfma_f32_16x16x32_bf16 v[120:123], v[146:149], v[170:173], v[120:123]
	v_mfma_f32_16x16x32_bf16 v[108:111], v[138:141], v[178:181], v[108:111]
	v_mfma_f32_16x16x32_bf16 v[104:107], v[146:149], v[178:181], v[104:107]
	v_mfma_f32_16x16x32_bf16 v[92:95], v[138:141], v[186:189], v[92:95]
	v_mfma_f32_16x16x32_bf16 v[88:91], v[146:149], v[186:189], v[88:91]
	v_mfma_f32_16x16x32_bf16 v[76:79], v[138:141], v[206:209], v[76:79]
	v_mfma_f32_16x16x32_bf16 v[72:75], v[146:149], v[206:209], v[72:75]
	s_setprio 0
	s_setprio 1
	v_mfma_f32_16x16x32_bf16 v[116:119], v[150:153], v[166:169], v[116:119]
	v_mfma_f32_16x16x32_bf16 v[112:115], v[158:161], v[166:169], v[112:115]
	v_mfma_f32_16x16x32_bf16 v[100:103], v[150:153], v[174:177], v[100:103]
	v_mfma_f32_16x16x32_bf16 v[96:99], v[158:161], v[174:177], v[96:99]
	v_mfma_f32_16x16x32_bf16 v[84:87], v[150:153], v[182:185], v[84:87]
	v_mfma_f32_16x16x32_bf16 v[80:83], v[158:161], v[182:185], v[80:83]
	v_mfma_f32_16x16x32_bf16 v[68:71], v[150:153], v[202:205], v[68:71]
	v_mfma_f32_16x16x32_bf16 v[64:67], v[158:161], v[202:205], v[64:67]
	v_mfma_f32_16x16x32_bf16 v[116:119], v[154:157], v[170:173], v[116:119]
	v_mfma_f32_16x16x32_bf16 v[112:115], v[162:165], v[170:173], v[112:115]
	v_mfma_f32_16x16x32_bf16 v[100:103], v[154:157], v[178:181], v[100:103]
	v_mfma_f32_16x16x32_bf16 v[96:99], v[162:165], v[178:181], v[96:99]
	v_mfma_f32_16x16x32_bf16 v[84:87], v[154:157], v[186:189], v[84:87]
	v_mfma_f32_16x16x32_bf16 v[80:83], v[162:165], v[186:189], v[80:83]
	v_mfma_f32_16x16x32_bf16 v[68:71], v[154:157], v[206:209], v[68:71]
	v_mfma_f32_16x16x32_bf16 v[64:67], v[162:165], v[206:209], v[64:67]
	s_setprio 0
	s_barrier
	s_add_i32 s90, s92, s33
	s_mov_b32 m0, s90
	ds_read_b128 v[166:169], v131 offset:16384
	ds_read_b128 v[170:173], v131 offset:17408
	ds_read_b128 v[174:177], v131 offset:18432
	ds_read_b128 v[178:181], v131 offset:19456
	ds_read_b128 v[182:185], v131 offset:20480
	ds_read_b128 v[186:189], v131 offset:21504
	ds_read_b128 v[202:205], v131 offset:22528
	ds_read_b128 v[206:209], v131 offset:23552
	global_load_lds_dwordx4 v192, s[22:23]
	s_add_i32 m0, s90, 0x2000
	s_nop 0
	global_load_lds_dwordx4 v132, s[22:23]
	s_add_i32 s22, s93, s33
	s_mov_b32 m0, s22
	s_nop 0
	global_load_lds_dwordx4 v192, s[56:57]
	s_add_i32 m0, s22, 0x2000
	s_nop 0
	global_load_lds_dwordx4 v132, s[56:57]
	s_mov_b32 m0, s0
	s_nop 0
	global_load_lds_dwordx4 v128, s[28:29]
	s_mov_b32 m0, s1
	s_nop 0
	global_load_lds_dwordx4 v130, s[28:29]
	s_waitcnt vmcnt(8)
	s_waitcnt lgkmcnt(0)
	s_barrier
	s_setprio 1
	s_waitcnt lgkmcnt(0)
	v_mfma_f32_16x16x32_bf16 v[60:63], v[134:137], v[166:169], v[60:63]
	v_mfma_f32_16x16x32_bf16 v[56:59], v[142:145], v[166:169], v[56:59]
	v_mfma_f32_16x16x32_bf16 v[44:47], v[134:137], v[174:177], v[44:47]
	v_mfma_f32_16x16x32_bf16 v[40:43], v[142:145], v[174:177], v[40:43]
	v_mfma_f32_16x16x32_bf16 v[28:31], v[134:137], v[182:185], v[28:31]
	v_mfma_f32_16x16x32_bf16 v[24:27], v[142:145], v[182:185], v[24:27]
	v_mfma_f32_16x16x32_bf16 v[12:15], v[134:137], v[202:205], v[12:15]
	v_mfma_f32_16x16x32_bf16 v[8:11], v[142:145], v[202:205], v[8:11]
	v_mfma_f32_16x16x32_bf16 v[60:63], v[138:141], v[170:173], v[60:63]
	v_mfma_f32_16x16x32_bf16 v[56:59], v[146:149], v[170:173], v[56:59]
	v_mfma_f32_16x16x32_bf16 v[44:47], v[138:141], v[178:181], v[44:47]
	v_mfma_f32_16x16x32_bf16 v[40:43], v[146:149], v[178:181], v[40:43]
	v_mfma_f32_16x16x32_bf16 v[28:31], v[138:141], v[186:189], v[28:31]
	v_mfma_f32_16x16x32_bf16 v[24:27], v[146:149], v[186:189], v[24:27]
	v_mfma_f32_16x16x32_bf16 v[12:15], v[138:141], v[206:209], v[12:15]
	v_mfma_f32_16x16x32_bf16 v[8:11], v[146:149], v[206:209], v[8:11]
	s_setprio 0
	s_setprio 1
	v_mfma_f32_16x16x32_bf16 v[52:55], v[150:153], v[166:169], v[52:55]
	v_mfma_f32_16x16x32_bf16 v[48:51], v[158:161], v[166:169], v[48:51]
	v_mfma_f32_16x16x32_bf16 v[36:39], v[150:153], v[174:177], v[36:39]
	v_mfma_f32_16x16x32_bf16 v[32:35], v[158:161], v[174:177], v[32:35]
	v_mfma_f32_16x16x32_bf16 v[20:23], v[150:153], v[182:185], v[20:23]
	v_mfma_f32_16x16x32_bf16 v[16:19], v[158:161], v[182:185], v[16:19]
	v_mfma_f32_16x16x32_bf16 v[4:7], v[150:153], v[202:205], v[4:7]
	v_mfma_f32_16x16x32_bf16 v[0:3], v[158:161], v[202:205], v[0:3]
	v_mfma_f32_16x16x32_bf16 v[52:55], v[154:157], v[170:173], v[52:55]
	v_mfma_f32_16x16x32_bf16 v[48:51], v[162:165], v[170:173], v[48:51]
	v_mfma_f32_16x16x32_bf16 v[36:39], v[154:157], v[178:181], v[36:39]
	v_mfma_f32_16x16x32_bf16 v[32:35], v[162:165], v[178:181], v[32:35]
	v_mfma_f32_16x16x32_bf16 v[20:23], v[154:157], v[186:189], v[20:23]
	v_mfma_f32_16x16x32_bf16 v[16:19], v[162:165], v[186:189], v[16:19]
	v_mfma_f32_16x16x32_bf16 v[4:7], v[154:157], v[206:209], v[4:7]
	v_mfma_f32_16x16x32_bf16 v[0:3], v[162:165], v[206:209], v[0:3]
	s_setprio 0
	s_barrier
	s_add_i32 s22, 0, 0x18000
	v_add_u32_e32 v133, s22, v129
	s_add_i32 s23, 0, 0x1c000
	ds_read_b128 v[134:137], v133
	ds_read_b128 v[138:141], v133 offset:1024
	ds_read_b128 v[142:145], v133 offset:2048
	ds_read_b128 v[146:149], v133 offset:3072
	v_add_u32_e32 v133, s23, v129
	ds_read_b128 v[150:153], v133
	ds_read_b128 v[154:157], v133 offset:1024
	ds_read_b128 v[158:161], v133 offset:2048
	ds_read_b128 v[162:165], v133 offset:3072
	s_mov_b32 m0, s34
	ds_read_b128 v[166:169], v131 offset:32768
	ds_read_b128 v[170:173], v131 offset:33792
	ds_read_b128 v[174:177], v131 offset:34816
	ds_read_b128 v[178:181], v131 offset:35840
	ds_read_b128 v[182:185], v131 offset:36864
	ds_read_b128 v[186:189], v131 offset:37888
	ds_read_b128 v[202:205], v131 offset:38912
	ds_read_b128 v[206:209], v131 offset:39936
	global_load_lds_dwordx4 v128, s[52:53]
	s_mov_b32 m0, s35
	s_nop 0
	global_load_lds_dwordx4 v130, s[52:53]
	s_waitcnt vmcnt(8)
	s_waitcnt lgkmcnt(0)
	s_barrier
	s_setprio 1
	s_waitcnt lgkmcnt(0)
	v_mfma_f32_16x16x32_bf16 v[124:127], v[134:137], v[166:169], v[124:127]
	v_mfma_f32_16x16x32_bf16 v[120:123], v[142:145], v[166:169], v[120:123]
	v_mfma_f32_16x16x32_bf16 v[108:111], v[134:137], v[174:177], v[108:111]
	v_mfma_f32_16x16x32_bf16 v[104:107], v[142:145], v[174:177], v[104:107]
	v_mfma_f32_16x16x32_bf16 v[92:95], v[134:137], v[182:185], v[92:95]
	v_mfma_f32_16x16x32_bf16 v[88:91], v[142:145], v[182:185], v[88:91]
	v_mfma_f32_16x16x32_bf16 v[76:79], v[134:137], v[202:205], v[76:79]
	v_mfma_f32_16x16x32_bf16 v[72:75], v[142:145], v[202:205], v[72:75]
	v_mfma_f32_16x16x32_bf16 v[124:127], v[138:141], v[170:173], v[124:127]
	v_mfma_f32_16x16x32_bf16 v[120:123], v[146:149], v[170:173], v[120:123]
	v_mfma_f32_16x16x32_bf16 v[108:111], v[138:141], v[178:181], v[108:111]
	v_mfma_f32_16x16x32_bf16 v[104:107], v[146:149], v[178:181], v[104:107]
	v_mfma_f32_16x16x32_bf16 v[92:95], v[138:141], v[186:189], v[92:95]
	v_mfma_f32_16x16x32_bf16 v[88:91], v[146:149], v[186:189], v[88:91]
	v_mfma_f32_16x16x32_bf16 v[76:79], v[138:141], v[206:209], v[76:79]
	v_mfma_f32_16x16x32_bf16 v[72:75], v[146:149], v[206:209], v[72:75]
	s_setprio 0
	s_setprio 1
	v_mfma_f32_16x16x32_bf16 v[116:119], v[150:153], v[166:169], v[116:119]
	v_mfma_f32_16x16x32_bf16 v[112:115], v[158:161], v[166:169], v[112:115]
	v_mfma_f32_16x16x32_bf16 v[100:103], v[150:153], v[174:177], v[100:103]
	v_mfma_f32_16x16x32_bf16 v[96:99], v[158:161], v[174:177], v[96:99]
	v_mfma_f32_16x16x32_bf16 v[84:87], v[150:153], v[182:185], v[84:87]
	v_mfma_f32_16x16x32_bf16 v[80:83], v[158:161], v[182:185], v[80:83]
	v_mfma_f32_16x16x32_bf16 v[68:71], v[150:153], v[202:205], v[68:71]
	v_mfma_f32_16x16x32_bf16 v[64:67], v[158:161], v[202:205], v[64:67]
	v_mfma_f32_16x16x32_bf16 v[116:119], v[154:157], v[170:173], v[116:119]
	v_mfma_f32_16x16x32_bf16 v[112:115], v[162:165], v[170:173], v[112:115]
	v_mfma_f32_16x16x32_bf16 v[100:103], v[154:157], v[178:181], v[100:103]
	v_mfma_f32_16x16x32_bf16 v[96:99], v[162:165], v[178:181], v[96:99]
	v_mfma_f32_16x16x32_bf16 v[84:87], v[154:157], v[186:189], v[84:87]
	v_mfma_f32_16x16x32_bf16 v[80:83], v[162:165], v[186:189], v[80:83]
	v_mfma_f32_16x16x32_bf16 v[68:71], v[154:157], v[206:209], v[68:71]
	v_mfma_f32_16x16x32_bf16 v[64:67], v[162:165], v[206:209], v[64:67]
	s_setprio 0
	s_barrier
;     __device__ __forceinline__ const char* a(const Unit& u) const { return (const char*)A + (size_t)u.pm * 2 * hA(); }
;     __device__ __forceinline__ const char* b(const Unit& u) const { return (const char*)Bt + (size_t)u.pn * 2 * hB() + (size_t)(u.pm >> gshift) * goff; }
;     __device__ __forceinline__ const char* a(const Unit& u) const { return (const char*)A + (size_t)u.pm * 2 * hA(); }
;     __device__ __forceinline__ const char* b(const Unit& u) const { return (const char*)Bt + (size_t)((u.pn >> 4) * 4096 + (u.pn & 15) * 16) * 1024 * 2 + (size_t)(u.pm >> 1) * 512; }
;     __device__ __forceinline__ const char* a(const Unit&) const { return (const char*)A; }
;     __device__ __forceinline__ const char* b(const Unit& u) const { return (const char*)Bt + ((size_t)(((u.pm >> 4) * 1024 + u.pn * 256) * 16 + (u.pm & 15)) * 512) * 2; }
;     __device__ __forceinline__ void operator()(const f32x4 (&acc)[2][2][4][2], const Unit& u, int wr, int wc, int fr, int fq) const {
;     ...
;             for (int m = 0; m < 4; ++m) { const int r = row0 + ai * HALF + m * 16;
;                 bf16_t* rowp = hm ? base + ((size_t)((r >> 12) * 8 + (colt >> 7)) * 4096 + (r & 4095)) * 128 + wc * 32 + 8 * fq : base + (size_t)r * ldc + col0;
;                 float rv = sc; if (RS == 1) rv *= rsv[ai][m]; if (RS == 2) rv *= __builtin_amdgcn_rsqf(rsv[ai][m] * (1.0f / DM) + EPS);
; #pragma unroll
;                 for (int bj = 0; bj < 2; ++bj) { f32x4 v0 = acc[ai][bj][m][0] * rv, v1 = acc[ai][bj][m][1] * rv;
;                     if (CS) { v0 = v0 * cv[bj][0]; v1 = v1 * cv[bj][1]; }
;                     if (ACT == 2) {
; #pragma unroll
;                         for (int e = 0; e < 4; ++e) { float a = v0[e] > 0.f ? v0[e] : 0.f, b = v1[e] > 0.f ? v1[e] : 0.f; v0[e] = a * a; v1[e] = b * b; } }
;                     if (k8) {
;                         u32x2 w8; w8.x = pk_fp8x4(v0); w8.y = pk_fp8x4(v1);
;                         *(u32x2*)((unsigned char*)base + ((size_t)((r >> 12) * 8 + (colt >> 7) + bj) * 4096 + (r & 4095)) * 128 + wc * 32 + 8 * fq) = w8;
;                     } else {
;                     u32x4 w; w.x = cvt_pk_bf16(v0[0], v0[1]); w.y = cvt_pk_bf16(v0[2], v0[3]); w.z = cvt_pk_bf16(v1[0], v1[1]); w.w = cvt_pk_bf16(v1[2], v1[3]);
;                     *(u32x4*)(rowp + bj * bstep) = w; } } }
	s_add_i32 s22, s22, s33
	s_mov_b32 m0, s22
	ds_read_b128 v[166:169], v131 offset:49152
	ds_read_b128 v[170:173], v131 offset:50176
	ds_read_b128 v[174:177], v131 offset:51200
	ds_read_b128 v[178:181], v131 offset:52224
	ds_read_b128 v[182:185], v131 offset:53248
	ds_read_b128 v[186:189], v131 offset:54272
	ds_read_b128 v[202:205], v131 offset:55296
	ds_read_b128 v[206:209], v131 offset:56320
	global_load_lds_dwordx4 v192, s[66:67]
	s_add_i32 m0, s22, 0x2000
	s_add_i32 s22, s23, s33
	global_load_lds_dwordx4 v132, s[66:67]
	s_mov_b32 m0, s22
	s_nop 0
	global_load_lds_dwordx4 v192, s[46:47]
	s_add_i32 m0, s22, 0x2000
	s_nop 0
	global_load_lds_dwordx4 v132, s[46:47]
	s_mov_b32 m0, s54
	s_nop 0
	global_load_lds_dwordx4 v128, s[26:27]
	s_mov_b32 m0, s55
	s_nop 0
	global_load_lds_dwordx4 v130, s[26:27]
	v_fmamk_f32 v248, v240, 0x3a000000, v227
	v_rsq_f32_e32 v248, v248
	s_nop 0
	v_pk_mul_f32 v[120:121], v[120:121], v[248:249] op_sel_hi:[1,0]
	v_pk_mul_f32 v[122:123], v[122:123], v[248:249] op_sel_hi:[1,0]
	v_pk_mul_f32 v[124:125], v[124:125], v[248:249] op_sel_hi:[1,0]
	v_pk_mul_f32 v[126:127], v[126:127], v[248:249] op_sel_hi:[1,0]
	v_max_f32_e32 v120, 0, v120
	v_max_f32_e32 v121, 0, v121
	v_max_f32_e32 v122, 0, v122
	v_max_f32_e32 v123, 0, v123
	v_max_f32_e32 v124, 0, v124
	v_max_f32_e32 v125, 0, v125
	v_max_f32_e32 v126, 0, v126
	v_max_f32_e32 v127, 0, v127
	v_pk_mul_f32 v[120:121], v[120:121], v[120:121]
	v_pk_mul_f32 v[122:123], v[122:123], v[122:123]
	v_pk_mul_f32 v[124:125], v[124:125], v[124:125]
	v_pk_mul_f32 v[126:127], v[126:127], v[126:127]
	v_cvt_pk_bf16_f32 v124, v124, v125
	v_cvt_pk_bf16_f32 v125, v126, v127
	v_cvt_pk_bf16_f32 v126, v120, v121
	v_cvt_pk_bf16_f32 v127, v122, v123
	global_store_dwordx4 v250, v[124:127], s[98:99] sc1
	v_pk_mul_f32 v[112:113], v[112:113], v[248:249] op_sel_hi:[1,0]
	v_pk_mul_f32 v[114:115], v[114:115], v[248:249] op_sel_hi:[1,0]
	v_pk_mul_f32 v[116:117], v[116:117], v[248:249] op_sel_hi:[1,0]
	v_pk_mul_f32 v[118:119], v[118:119], v[248:249] op_sel_hi:[1,0]
	v_max_f32_e32 v112, 0, v112
	v_max_f32_e32 v113, 0, v113
	v_max_f32_e32 v114, 0, v114
	v_max_f32_e32 v115, 0, v115
	v_max_f32_e32 v116, 0, v116
	v_max_f32_e32 v117, 0, v117
	v_max_f32_e32 v118, 0, v118
	v_max_f32_e32 v119, 0, v119
	v_pk_mul_f32 v[112:113], v[112:113], v[112:113]
	v_pk_mul_f32 v[114:115], v[114:115], v[114:115]
	v_pk_mul_f32 v[116:117], v[116:117], v[116:117]
	v_pk_mul_f32 v[118:119], v[118:119], v[118:119]
	v_cvt_pk_bf16_f32 v116, v116, v117
	v_cvt_pk_bf16_f32 v117, v118, v119
	v_cvt_pk_bf16_f32 v118, v112, v113
	v_cvt_pk_bf16_f32 v119, v114, v115
	global_store_dwordx4 v250, v[116:119], s[98:99] offset:256 sc1
	s_add_u32 s98, s98, 0x40000
	s_addc_u32 s99, s99, 0
	v_fmamk_f32 v248, v241, 0x3a000000, v227
	v_rsq_f32_e32 v248, v248
	s_nop 0
	v_pk_mul_f32 v[104:105], v[104:105], v[248:249] op_sel_hi:[1,0]
	v_pk_mul_f32 v[106:107], v[106:107], v[248:249] op_sel_hi:[1,0]
	v_pk_mul_f32 v[108:109], v[108:109], v[248:249] op_sel_hi:[1,0]
	v_pk_mul_f32 v[110:111], v[110:111], v[248:249] op_sel_hi:[1,0]
	v_max_f32_e32 v104, 0, v104
	v_max_f32_e32 v105, 0, v105
	v_max_f32_e32 v106, 0, v106
	v_max_f32_e32 v107, 0, v107
	v_max_f32_e32 v108, 0, v108
	v_max_f32_e32 v109, 0, v109
	v_max_f32_e32 v110, 0, v110
	v_max_f32_e32 v111, 0, v111
	v_pk_mul_f32 v[104:105], v[104:105], v[104:105]
	v_pk_mul_f32 v[106:107], v[106:107], v[106:107]
	v_pk_mul_f32 v[108:109], v[108:109], v[108:109]
	v_pk_mul_f32 v[110:111], v[110:111], v[110:111]
	v_cvt_pk_bf16_f32 v108, v108, v109
	v_cvt_pk_bf16_f32 v109, v110, v111
	v_cvt_pk_bf16_f32 v110, v104, v105
	v_cvt_pk_bf16_f32 v111, v106, v107
	global_store_dwordx4 v250, v[108:111], s[98:99] sc1
	v_pk_mul_f32 v[96:97], v[96:97], v[248:249] op_sel_hi:[1,0]
	v_pk_mul_f32 v[98:99], v[98:99], v[248:249] op_sel_hi:[1,0]
	v_pk_mul_f32 v[100:101], v[100:101], v[248:249] op_sel_hi:[1,0]
	v_pk_mul_f32 v[102:103], v[102:103], v[248:249] op_sel_hi:[1,0]
	v_max_f32_e32 v96, 0, v96
	v_max_f32_e32 v97, 0, v97
	v_max_f32_e32 v98, 0, v98
	v_max_f32_e32 v99, 0, v99
	v_max_f32_e32 v100, 0, v100
	v_max_f32_e32 v101, 0, v101
	v_max_f32_e32 v102, 0, v102
	v_max_f32_e32 v103, 0, v103
	v_pk_mul_f32 v[96:97], v[96:97], v[96:97]
	v_pk_mul_f32 v[98:99], v[98:99], v[98:99]
	v_pk_mul_f32 v[100:101], v[100:101], v[100:101]
	v_pk_mul_f32 v[102:103], v[102:103], v[102:103]
	v_cvt_pk_bf16_f32 v100, v100, v101
	v_cvt_pk_bf16_f32 v101, v102, v103
	v_cvt_pk_bf16_f32 v102, v96, v97
	v_cvt_pk_bf16_f32 v103, v98, v99
	global_store_dwordx4 v250, v[100:103], s[98:99] offset:256 sc1
	s_add_u32 s98, s98, 0x40000
	s_addc_u32 s99, s99, 0
	s_waitcnt vmcnt(12)
	s_waitcnt lgkmcnt(0)
	s_barrier
;     __device__ __forceinline__ const char* a(const Unit& u) const { return (const char*)A + (size_t)u.pm * 2 * hA(); }
;     __device__ __forceinline__ const char* b(const Unit& u) const { return (const char*)Bt + (size_t)u.pn * 2 * hB() + (size_t)(u.pm >> gshift) * goff; }
;     __device__ __forceinline__ const char* a(const Unit& u) const { return (const char*)A + (size_t)u.pm * 2 * hA(); }
;     __device__ __forceinline__ const char* b(const Unit& u) const { return (const char*)Bt + (size_t)((u.pn >> 4) * 4096 + (u.pn & 15) * 16) * 1024 * 2 + (size_t)(u.pm >> 1) * 512; }
;     __device__ __forceinline__ const char* a(const Unit&) const { return (const char*)A; }
;     __device__ __forceinline__ const char* b(const Unit& u) const { return (const char*)Bt + ((size_t)(((u.pm >> 4) * 1024 + u.pn * 256) * 16 + (u.pm & 15)) * 512) * 2; }
;     __device__ __forceinline__ void operator()(const f32x4 (&acc)[2][2][4][2], const Unit& u, int wr, int wc, int fr, int fq) const {
;     ...
;             for (int m = 0; m < 4; ++m) { const int r = row0 + ai * HALF + m * 16;
;                 bf16_t* rowp = hm ? base + ((size_t)((r >> 12) * 8 + (colt >> 7)) * 4096 + (r & 4095)) * 128 + wc * 32 + 8 * fq : base + (size_t)r * ldc + col0;
;                 float rv = sc; if (RS == 1) rv *= rsv[ai][m]; if (RS == 2) rv *= __builtin_amdgcn_rsqf(rsv[ai][m] * (1.0f / DM) + EPS);
; #pragma unroll
;                 for (int bj = 0; bj < 2; ++bj) { f32x4 v0 = acc[ai][bj][m][0] * rv, v1 = acc[ai][bj][m][1] * rv;
;                     if (CS) { v0 = v0 * cv[bj][0]; v1 = v1 * cv[bj][1]; }
;                     if (ACT == 2) {
; #pragma unroll
;                         for (int e = 0; e < 4; ++e) { float a = v0[e] > 0.f ? v0[e] : 0.f, b = v1[e] > 0.f ? v1[e] : 0.f; v0[e] = a * a; v1[e] = b * b; } }
;                     if (k8) {
;                         u32x2 w8; w8.x = pk_fp8x4(v0); w8.y = pk_fp8x4(v1);
;                         *(u32x2*)((unsigned char*)base + ((size_t)((r >> 12) * 8 + (colt >> 7) + bj) * 4096 + (r & 4095)) * 128 + wc * 32 + 8 * fq) = w8;
;                     } else {
;                     u32x4 w; w.x = cvt_pk_bf16(v0[0], v0[1]); w.y = cvt_pk_bf16(v0[2], v0[3]); w.z = cvt_pk_bf16(v1[0], v1[1]); w.w = cvt_pk_bf16(v1[2], v1[3]);
;                     *(u32x4*)(rowp + bj * bstep) = w; } } }
	s_setprio 1
	s_waitcnt lgkmcnt(0)
	v_mfma_f32_16x16x32_bf16 v[60:63], v[134:137], v[166:169], v[60:63]
	v_fmamk_f32 v248, v242, 0x3a000000, v227
	v_rsq_f32_e32 v248, v248
	s_nop 0
	v_mfma_f32_16x16x32_bf16 v[56:59], v[142:145], v[166:169], v[56:59]
	v_pk_mul_f32 v[88:89], v[88:89], v[248:249] op_sel_hi:[1,0]
	v_pk_mul_f32 v[90:91], v[90:91], v[248:249] op_sel_hi:[1,0]
	v_pk_mul_f32 v[92:93], v[92:93], v[248:249] op_sel_hi:[1,0]
	v_mfma_f32_16x16x32_bf16 v[44:47], v[134:137], v[174:177], v[44:47]
	v_pk_mul_f32 v[94:95], v[94:95], v[248:249] op_sel_hi:[1,0]
	v_max_f32_e32 v88, 0, v88
	v_max_f32_e32 v89, 0, v89
	v_mfma_f32_16x16x32_bf16 v[40:43], v[142:145], v[174:177], v[40:43]
	v_max_f32_e32 v90, 0, v90
	v_max_f32_e32 v91, 0, v91
	v_max_f32_e32 v92, 0, v92
	v_mfma_f32_16x16x32_bf16 v[28:31], v[134:137], v[182:185], v[28:31]
	v_max_f32_e32 v93, 0, v93
	v_max_f32_e32 v94, 0, v94
	v_max_f32_e32 v95, 0, v95
	v_mfma_f32_16x16x32_bf16 v[24:27], v[142:145], v[182:185], v[24:27]
	v_pk_mul_f32 v[88:89], v[88:89], v[88:89]
	v_pk_mul_f32 v[90:91], v[90:91], v[90:91]
	v_pk_mul_f32 v[92:93], v[92:93], v[92:93]
	v_mfma_f32_16x16x32_bf16 v[12:15], v[134:137], v[202:205], v[12:15]
	v_pk_mul_f32 v[94:95], v[94:95], v[94:95]
	v_cvt_pk_bf16_f32 v92, v92, v93
	v_cvt_pk_bf16_f32 v93, v94, v95
	v_mfma_f32_16x16x32_bf16 v[8:11], v[142:145], v[202:205], v[8:11]
	v_cvt_pk_bf16_f32 v94, v88, v89
	v_cvt_pk_bf16_f32 v95, v90, v91
	global_store_dwordx4 v250, v[92:95], s[98:99] sc1
	v_mfma_f32_16x16x32_bf16 v[60:63], v[138:141], v[170:173], v[60:63]
	v_pk_mul_f32 v[80:81], v[80:81], v[248:249] op_sel_hi:[1,0]
	v_pk_mul_f32 v[82:83], v[82:83], v[248:249] op_sel_hi:[1,0]
	v_pk_mul_f32 v[84:85], v[84:85], v[248:249] op_sel_hi:[1,0]
	v_mfma_f32_16x16x32_bf16 v[56:59], v[146:149], v[170:173], v[56:59]
	v_pk_mul_f32 v[86:87], v[86:87], v[248:249] op_sel_hi:[1,0]
	v_max_f32_e32 v80, 0, v80
	v_max_f32_e32 v81, 0, v81
	v_mfma_f32_16x16x32_bf16 v[44:47], v[138:141], v[178:181], v[44:47]
	v_max_f32_e32 v82, 0, v82
	v_max_f32_e32 v83, 0, v83
	v_max_f32_e32 v84, 0, v84
	v_mfma_f32_16x16x32_bf16 v[40:43], v[146:149], v[178:181], v[40:43]
	v_max_f32_e32 v85, 0, v85
	v_max_f32_e32 v86, 0, v86
	v_max_f32_e32 v87, 0, v87
	v_mfma_f32_16x16x32_bf16 v[28:31], v[138:141], v[186:189], v[28:31]
	v_pk_mul_f32 v[80:81], v[80:81], v[80:81]
	v_pk_mul_f32 v[82:83], v[82:83], v[82:83]
	v_pk_mul_f32 v[84:85], v[84:85], v[84:85]
	v_mfma_f32_16x16x32_bf16 v[24:27], v[146:149], v[186:189], v[24:27]
	v_pk_mul_f32 v[86:87], v[86:87], v[86:87]
	v_cvt_pk_bf16_f32 v84, v84, v85
	v_cvt_pk_bf16_f32 v85, v86, v87
	v_mfma_f32_16x16x32_bf16 v[12:15], v[138:141], v[206:209], v[12:15]
	v_cvt_pk_bf16_f32 v86, v80, v81
	v_cvt_pk_bf16_f32 v87, v82, v83
	global_store_dwordx4 v250, v[84:87], s[98:99] offset:256 sc1
	v_mfma_f32_16x16x32_bf16 v[8:11], v[146:149], v[206:209], v[8:11]
	s_add_u32 s98, s98, 0x40000
	s_addc_u32 s99, s99, 0
	v_fmamk_f32 v248, v243, 0x3a000000, v227
	s_setprio 0
	s_setprio 1
	v_mfma_f32_16x16x32_bf16 v[52:55], v[150:153], v[166:169], v[52:55]
	v_rsq_f32_e32 v248, v248
	s_nop 0
	v_pk_mul_f32 v[72:73], v[72:73], v[248:249] op_sel_hi:[1,0]
	v_mfma_f32_16x16x32_bf16 v[48:51], v[158:161], v[166:169], v[48:51]
	v_pk_mul_f32 v[74:75], v[74:75], v[248:249] op_sel_hi:[1,0]
	v_pk_mul_f32 v[76:77], v[76:77], v[248:249] op_sel_hi:[1,0]
	v_pk_mul_f32 v[78:79], v[78:79], v[248:249] op_sel_hi:[1,0]
	v_mfma_f32_16x16x32_bf16 v[36:39], v[150:153], v[174:177], v[36:39]
	v_max_f32_e32 v72, 0, v72
	v_max_f32_e32 v73, 0, v73
	v_max_f32_e32 v74, 0, v74
	v_mfma_f32_16x16x32_bf16 v[32:35], v[158:161], v[174:177], v[32:35]
	v_max_f32_e32 v75, 0, v75
	v_max_f32_e32 v76, 0, v76
	v_max_f32_e32 v77, 0, v77
	v_mfma_f32_16x16x32_bf16 v[20:23], v[150:153], v[182:185], v[20:23]
	v_max_f32_e32 v78, 0, v78
	v_max_f32_e32 v79, 0, v79
	v_pk_mul_f32 v[72:73], v[72:73], v[72:73]
	v_mfma_f32_16x16x32_bf16 v[16:19], v[158:161], v[182:185], v[16:19]
	v_pk_mul_f32 v[74:75], v[74:75], v[74:75]
	v_pk_mul_f32 v[76:77], v[76:77], v[76:77]
	v_pk_mul_f32 v[78:79], v[78:79], v[78:79]
	v_mfma_f32_16x16x32_bf16 v[4:7], v[150:153], v[202:205], v[4:7]
	v_cvt_pk_bf16_f32 v76, v76, v77
	v_cvt_pk_bf16_f32 v77, v78, v79
	v_cvt_pk_bf16_f32 v78, v72, v73
	v_mfma_f32_16x16x32_bf16 v[0:3], v[158:161], v[202:205], v[0:3]
	v_cvt_pk_bf16_f32 v79, v74, v75
	global_store_dwordx4 v250, v[76:79], s[98:99] sc1
	v_pk_mul_f32 v[64:65], v[64:65], v[248:249] op_sel_hi:[1,0]
	v_mfma_f32_16x16x32_bf16 v[52:55], v[154:157], v[170:173], v[52:55]
	v_pk_mul_f32 v[66:67], v[66:67], v[248:249] op_sel_hi:[1,0]
	v_pk_mul_f32 v[68:69], v[68:69], v[248:249] op_sel_hi:[1,0]
	v_pk_mul_f32 v[70:71], v[70:71], v[248:249] op_sel_hi:[1,0]
	v_mfma_f32_16x16x32_bf16 v[48:51], v[162:165], v[170:173], v[48:51]
	v_max_f32_e32 v64, 0, v64
	v_max_f32_e32 v65, 0, v65
	v_max_f32_e32 v66, 0, v66
	v_mfma_f32_16x16x32_bf16 v[36:39], v[154:157], v[178:181], v[36:39]
	v_max_f32_e32 v67, 0, v67
	v_max_f32_e32 v68, 0, v68
	v_max_f32_e32 v69, 0, v69
	v_mfma_f32_16x16x32_bf16 v[32:35], v[162:165], v[178:181], v[32:35]
	v_max_f32_e32 v70, 0, v70
	v_max_f32_e32 v71, 0, v71
	v_pk_mul_f32 v[64:65], v[64:65], v[64:65]
	v_mfma_f32_16x16x32_bf16 v[20:23], v[154:157], v[186:189], v[20:23]
	v_pk_mul_f32 v[66:67], v[66:67], v[66:67]
	v_pk_mul_f32 v[68:69], v[68:69], v[68:69]
	v_pk_mul_f32 v[70:71], v[70:71], v[70:71]
	v_mfma_f32_16x16x32_bf16 v[16:19], v[162:165], v[186:189], v[16:19]
	v_cvt_pk_bf16_f32 v68, v68, v69
	v_cvt_pk_bf16_f32 v69, v70, v71
	v_cvt_pk_bf16_f32 v70, v64, v65
	v_mfma_f32_16x16x32_bf16 v[4:7], v[154:157], v[206:209], v[4:7]
	v_cvt_pk_bf16_f32 v71, v66, v67
	global_store_dwordx4 v250, v[68:71], s[98:99] offset:256 sc1
	s_add_u32 s98, s98, 0x40000
	v_mfma_f32_16x16x32_bf16 v[0:3], v[162:165], v[206:209], v[0:3]
	s_addc_u32 s99, s99, 0
	s_setprio 0
	s_barrier
;     __device__ __forceinline__ const char* a(const Unit& u) const { return (const char*)A + (size_t)u.pm * 2 * hA(); }
;     __device__ __forceinline__ const char* b(const Unit& u) const { return (const char*)Bt + (size_t)u.pn * 2 * hB() + (size_t)(u.pm >> gshift) * goff; }
;     __device__ __forceinline__ const char* a(const Unit& u) const { return (const char*)A + (size_t)u.pm * 2 * hA(); }
;     __device__ __forceinline__ const char* b(const Unit& u) const { return (const char*)Bt + (size_t)((u.pn >> 4) * 4096 + (u.pn & 15) * 16) * 1024 * 2 + (size_t)(u.pm >> 1) * 512; }
;     __device__ __forceinline__ const char* a(const Unit&) const { return (const char*)A; }
;     __device__ __forceinline__ const char* b(const Unit& u) const { return (const char*)Bt + ((size_t)(((u.pm >> 4) * 1024 + u.pn * 256) * 16 + (u.pm & 15)) * 512) * 2; }
;     __device__ __forceinline__ void operator()(const f32x4 (&acc)[2][2][4][2], const Unit& u, int wr, int wc, int fr, int fq) const {
;     ...
;             for (int m = 0; m < 4; ++m) { const int r = row0 + ai * HALF + m * 16;
;                 bf16_t* rowp = hm ? base + ((size_t)((r >> 12) * 8 + (colt >> 7)) * 4096 + (r & 4095)) * 128 + wc * 32 + 8 * fq : base + (size_t)r * ldc + col0;
;                 float rv = sc; if (RS == 1) rv *= rsv[ai][m]; if (RS == 2) rv *= __builtin_amdgcn_rsqf(rsv[ai][m] * (1.0f / DM) + EPS);
; #pragma unroll
;                 for (int bj = 0; bj < 2; ++bj) { f32x4 v0 = acc[ai][bj][m][0] * rv, v1 = acc[ai][bj][m][1] * rv;
;                     if (CS) { v0 = v0 * cv[bj][0]; v1 = v1 * cv[bj][1]; }
;                     if (ACT == 2) {
; #pragma unroll
;                         for (int e = 0; e < 4; ++e) { float a = v0[e] > 0.f ? v0[e] : 0.f, b = v1[e] > 0.f ? v1[e] : 0.f; v0[e] = a * a; v1[e] = b * b; } }
;                     if (k8) {
;                         u32x2 w8; w8.x = pk_fp8x4(v0); w8.y = pk_fp8x4(v1);
;                         *(u32x2*)((unsigned char*)base + ((size_t)((r >> 12) * 8 + (colt >> 7) + bj) * 4096 + (r & 4095)) * 128 + wc * 32 + 8 * fq) = w8;
;                     } else {
;                     u32x4 w; w.x = cvt_pk_bf16(v0[0], v0[1]); w.y = cvt_pk_bf16(v0[2], v0[3]); w.z = cvt_pk_bf16(v1[0], v1[1]); w.w = cvt_pk_bf16(v1[2], v1[3]);
;                     *(u32x4*)(rowp + bj * bstep) = w; } } }
	s_nop 7
	v_fmamk_f32 v248, v244, 0x3a000000, v227
	v_rsq_f32_e32 v248, v248
	s_nop 0
	v_pk_mul_f32 v[56:57], v[56:57], v[248:249] op_sel_hi:[1,0]
	v_pk_mul_f32 v[58:59], v[58:59], v[248:249] op_sel_hi:[1,0]
	v_pk_mul_f32 v[60:61], v[60:61], v[248:249] op_sel_hi:[1,0]
	v_pk_mul_f32 v[62:63], v[62:63], v[248:249] op_sel_hi:[1,0]
	v_max_f32_e32 v56, 0, v56
	v_max_f32_e32 v57, 0, v57
	v_max_f32_e32 v58, 0, v58
	v_max_f32_e32 v59, 0, v59
	v_max_f32_e32 v60, 0, v60
	v_max_f32_e32 v61, 0, v61
	v_max_f32_e32 v62, 0, v62
	v_max_f32_e32 v63, 0, v63
	v_pk_mul_f32 v[56:57], v[56:57], v[56:57]
	v_pk_mul_f32 v[58:59], v[58:59], v[58:59]
	v_pk_mul_f32 v[60:61], v[60:61], v[60:61]
	v_pk_mul_f32 v[62:63], v[62:63], v[62:63]
	v_cvt_pk_bf16_f32 v60, v60, v61
	v_cvt_pk_bf16_f32 v61, v62, v63
	v_cvt_pk_bf16_f32 v62, v56, v57
	v_cvt_pk_bf16_f32 v63, v58, v59
	global_store_dwordx4 v250, v[60:63], s[100:101]
	v_pk_mul_f32 v[48:49], v[48:49], v[248:249] op_sel_hi:[1,0]
	v_pk_mul_f32 v[50:51], v[50:51], v[248:249] op_sel_hi:[1,0]
	v_pk_mul_f32 v[52:53], v[52:53], v[248:249] op_sel_hi:[1,0]
	v_pk_mul_f32 v[54:55], v[54:55], v[248:249] op_sel_hi:[1,0]
	v_max_f32_e32 v48, 0, v48
	v_max_f32_e32 v49, 0, v49
	v_max_f32_e32 v50, 0, v50
	v_max_f32_e32 v51, 0, v51
	v_max_f32_e32 v52, 0, v52
	v_max_f32_e32 v53, 0, v53
	v_max_f32_e32 v54, 0, v54
	v_max_f32_e32 v55, 0, v55
	v_pk_mul_f32 v[48:49], v[48:49], v[48:49]
	v_pk_mul_f32 v[50:51], v[50:51], v[50:51]
	v_pk_mul_f32 v[52:53], v[52:53], v[52:53]
	v_pk_mul_f32 v[54:55], v[54:55], v[54:55]
	v_cvt_pk_bf16_f32 v52, v52, v53
	v_cvt_pk_bf16_f32 v53, v54, v55
	v_cvt_pk_bf16_f32 v54, v48, v49
	v_cvt_pk_bf16_f32 v55, v50, v51
	global_store_dwordx4 v250, v[52:55], s[100:101] offset:256
	s_add_u32 s100, s100, 0x40000
	s_addc_u32 s101, s101, 0
	v_fmamk_f32 v248, v245, 0x3a000000, v227
	v_rsq_f32_e32 v248, v248
	s_nop 0
	v_pk_mul_f32 v[40:41], v[40:41], v[248:249] op_sel_hi:[1,0]
	v_pk_mul_f32 v[42:43], v[42:43], v[248:249] op_sel_hi:[1,0]
	v_pk_mul_f32 v[44:45], v[44:45], v[248:249] op_sel_hi:[1,0]
	v_pk_mul_f32 v[46:47], v[46:47], v[248:249] op_sel_hi:[1,0]
	v_max_f32_e32 v40, 0, v40
	v_max_f32_e32 v41, 0, v41
	v_max_f32_e32 v42, 0, v42
	v_max_f32_e32 v43, 0, v43
	v_max_f32_e32 v44, 0, v44
	v_max_f32_e32 v45, 0, v45
	v_max_f32_e32 v46, 0, v46
	v_max_f32_e32 v47, 0, v47
	v_pk_mul_f32 v[40:41], v[40:41], v[40:41]
	v_pk_mul_f32 v[42:43], v[42:43], v[42:43]
	v_pk_mul_f32 v[44:45], v[44:45], v[44:45]
	v_pk_mul_f32 v[46:47], v[46:47], v[46:47]
	v_cvt_pk_bf16_f32 v44, v44, v45
	v_cvt_pk_bf16_f32 v45, v46, v47
	v_cvt_pk_bf16_f32 v46, v40, v41
	v_cvt_pk_bf16_f32 v47, v42, v43
	global_store_dwordx4 v250, v[44:47], s[100:101]
	v_pk_mul_f32 v[32:33], v[32:33], v[248:249] op_sel_hi:[1,0]
	v_pk_mul_f32 v[34:35], v[34:35], v[248:249] op_sel_hi:[1,0]
	v_pk_mul_f32 v[36:37], v[36:37], v[248:249] op_sel_hi:[1,0]
	v_pk_mul_f32 v[38:39], v[38:39], v[248:249] op_sel_hi:[1,0]
	v_max_f32_e32 v32, 0, v32
	v_max_f32_e32 v33, 0, v33
	v_max_f32_e32 v34, 0, v34
	v_max_f32_e32 v35, 0, v35
	v_max_f32_e32 v36, 0, v36
	v_max_f32_e32 v37, 0, v37
	v_max_f32_e32 v38, 0, v38
	v_max_f32_e32 v39, 0, v39
	v_pk_mul_f32 v[32:33], v[32:33], v[32:33]
	v_pk_mul_f32 v[34:35], v[34:35], v[34:35]
	v_pk_mul_f32 v[36:37], v[36:37], v[36:37]
	v_pk_mul_f32 v[38:39], v[38:39], v[38:39]
	v_cvt_pk_bf16_f32 v36, v36, v37
	v_cvt_pk_bf16_f32 v37, v38, v39
	v_cvt_pk_bf16_f32 v38, v32, v33
	v_cvt_pk_bf16_f32 v39, v34, v35
	global_store_dwordx4 v250, v[36:39], s[100:101] offset:256
	s_add_u32 s100, s100, 0x40000
;     __device__ __forceinline__ const char* a(const Unit& u) const { return (const char*)A + (size_t)u.pm * 2 * hA(); }
;     __device__ __forceinline__ const char* b(const Unit& u) const { return (const char*)Bt + (size_t)u.pn * 2 * hB() + (size_t)(u.pm >> gshift) * goff; }
;     __device__ __forceinline__ const char* a(const Unit& u) const { return (const char*)A + (size_t)u.pm * 2 * hA(); }
;     __device__ __forceinline__ const char* b(const Unit& u) const { return (const char*)Bt + (size_t)((u.pn >> 4) * 4096 + (u.pn & 15) * 16) * 1024 * 2 + (size_t)(u.pm >> 1) * 512; }
;     __device__ __forceinline__ const char* a(const Unit&) const { return (const char*)A; }
; #define PG8_WAIT_V(n) asm volatile("s_waitcnt vmcnt(" #n ")" ::: "memory")
; #define PG8_BAR __builtin_amdgcn_s_barrier()
;     __device__ __forceinline__ void operator()(const f32x4 (&acc)[2][2][4][2], const Unit& u, int wr, int wc, int fr, int fq) const {
;     ...
;             for (int m = 0; m < 4; ++m) { const int r = row0 + ai * HALF + m * 16;
;                 bf16_t* rowp = hm ? base + ((size_t)((r >> 12) * 8 + (colt >> 7)) * 4096 + (r & 4095)) * 128 + wc * 32 + 8 * fq : base + (size_t)r * ldc + col0;
;                 float rv = sc; if (RS == 1) rv *= rsv[ai][m]; if (RS == 2) rv *= __builtin_amdgcn_rsqf(rsv[ai][m] * (1.0f / DM) + EPS);
; #pragma unroll
;                 for (int bj = 0; bj < 2; ++bj) { f32x4 v0 = acc[ai][bj][m][0] * rv, v1 = acc[ai][bj][m][1] * rv;
;                     if (CS) { v0 = v0 * cv[bj][0]; v1 = v1 * cv[bj][1]; }
;                     if (ACT == 2) {
; #pragma unroll
;                         for (int e = 0; e < 4; ++e) { float a = v0[e] > 0.f ? v0[e] : 0.f, b = v1[e] > 0.f ? v1[e] : 0.f; v0[e] = a * a; v1[e] = b * b; } }
;                     if (k8) {
;                         u32x2 w8; w8.x = pk_fp8x4(v0); w8.y = pk_fp8x4(v1);
;                         *(u32x2*)((unsigned char*)base + ((size_t)((r >> 12) * 8 + (colt >> 7) + bj) * 4096 + (r & 4095)) * 128 + wc * 32 + 8 * fq) = w8;
;                     } else {
;                     u32x4 w; w.x = cvt_pk_bf16(v0[0], v0[1]); w.y = cvt_pk_bf16(v0[2], v0[3]); w.z = cvt_pk_bf16(v1[0], v1[1]); w.w = cvt_pk_bf16(v1[2], v1[3]);
;                     *(u32x4*)(rowp + bj * bstep) = w; } } }
;     ...
;     if constexpr (!Epi::AFTER_DRAIN) PG8_WAIT_V(0);
;     if constexpr (!ALIGN_EPI) { if (wr == 0) PG8_BAR; }
;     PG8_BAR;
	s_addc_u32 s101, s101, 0
	v_fmamk_f32 v248, v246, 0x3a000000, v227
	v_rsq_f32_e32 v248, v248
	s_nop 0
	v_pk_mul_f32 v[24:25], v[24:25], v[248:249] op_sel_hi:[1,0]
	v_pk_mul_f32 v[26:27], v[26:27], v[248:249] op_sel_hi:[1,0]
	v_pk_mul_f32 v[28:29], v[28:29], v[248:249] op_sel_hi:[1,0]
	v_pk_mul_f32 v[30:31], v[30:31], v[248:249] op_sel_hi:[1,0]
	v_max_f32_e32 v24, 0, v24
	v_max_f32_e32 v25, 0, v25
	v_max_f32_e32 v26, 0, v26
	v_max_f32_e32 v27, 0, v27
	v_max_f32_e32 v28, 0, v28
	v_max_f32_e32 v29, 0, v29
	v_max_f32_e32 v30, 0, v30
	v_max_f32_e32 v31, 0, v31
	v_pk_mul_f32 v[24:25], v[24:25], v[24:25]
	v_pk_mul_f32 v[26:27], v[26:27], v[26:27]
	v_pk_mul_f32 v[28:29], v[28:29], v[28:29]
	v_pk_mul_f32 v[30:31], v[30:31], v[30:31]
	v_cvt_pk_bf16_f32 v28, v28, v29
	v_cvt_pk_bf16_f32 v29, v30, v31
	v_cvt_pk_bf16_f32 v30, v24, v25
	v_cvt_pk_bf16_f32 v31, v26, v27
	global_store_dwordx4 v250, v[28:31], s[100:101]
	v_pk_mul_f32 v[16:17], v[16:17], v[248:249] op_sel_hi:[1,0]
	v_pk_mul_f32 v[18:19], v[18:19], v[248:249] op_sel_hi:[1,0]
	v_pk_mul_f32 v[20:21], v[20:21], v[248:249] op_sel_hi:[1,0]
	v_pk_mul_f32 v[22:23], v[22:23], v[248:249] op_sel_hi:[1,0]
	v_max_f32_e32 v16, 0, v16
	v_max_f32_e32 v17, 0, v17
	v_max_f32_e32 v18, 0, v18
	v_max_f32_e32 v19, 0, v19
	v_max_f32_e32 v20, 0, v20
	v_max_f32_e32 v21, 0, v21
	v_max_f32_e32 v22, 0, v22
	v_max_f32_e32 v23, 0, v23
	v_pk_mul_f32 v[16:17], v[16:17], v[16:17]
	v_pk_mul_f32 v[18:19], v[18:19], v[18:19]
	v_pk_mul_f32 v[20:21], v[20:21], v[20:21]
	v_pk_mul_f32 v[22:23], v[22:23], v[22:23]
	v_cvt_pk_bf16_f32 v20, v20, v21
	v_cvt_pk_bf16_f32 v21, v22, v23
	v_cvt_pk_bf16_f32 v22, v16, v17
	v_cvt_pk_bf16_f32 v23, v18, v19
	global_store_dwordx4 v250, v[20:23], s[100:101] offset:256
	s_add_u32 s100, s100, 0x40000
	s_addc_u32 s101, s101, 0
	v_fmamk_f32 v248, v247, 0x3a000000, v227
	v_rsq_f32_e32 v248, v248
	s_nop 0
	v_pk_mul_f32 v[8:9], v[8:9], v[248:249] op_sel_hi:[1,0]
	v_pk_mul_f32 v[10:11], v[10:11], v[248:249] op_sel_hi:[1,0]
	v_pk_mul_f32 v[12:13], v[12:13], v[248:249] op_sel_hi:[1,0]
	v_pk_mul_f32 v[14:15], v[14:15], v[248:249] op_sel_hi:[1,0]
	v_max_f32_e32 v8, 0, v8
	v_max_f32_e32 v9, 0, v9
	v_max_f32_e32 v10, 0, v10
	v_max_f32_e32 v11, 0, v11
	v_max_f32_e32 v12, 0, v12
	v_max_f32_e32 v13, 0, v13
	v_max_f32_e32 v14, 0, v14
	v_max_f32_e32 v15, 0, v15
	v_pk_mul_f32 v[8:9], v[8:9], v[8:9]
	v_pk_mul_f32 v[10:11], v[10:11], v[10:11]
	v_pk_mul_f32 v[12:13], v[12:13], v[12:13]
	v_pk_mul_f32 v[14:15], v[14:15], v[14:15]
	v_cvt_pk_bf16_f32 v12, v12, v13
	v_cvt_pk_bf16_f32 v13, v14, v15
	v_cvt_pk_bf16_f32 v14, v8, v9
	v_cvt_pk_bf16_f32 v15, v10, v11
	global_store_dwordx4 v250, v[12:15], s[100:101]
	v_pk_mul_f32 v[0:1], v[0:1], v[248:249] op_sel_hi:[1,0]
	v_pk_mul_f32 v[2:3], v[2:3], v[248:249] op_sel_hi:[1,0]
	v_pk_mul_f32 v[4:5], v[4:5], v[248:249] op_sel_hi:[1,0]
	v_pk_mul_f32 v[6:7], v[6:7], v[248:249] op_sel_hi:[1,0]
	v_max_f32_e32 v0, 0, v0
	v_max_f32_e32 v1, 0, v1
	v_max_f32_e32 v2, 0, v2
	v_max_f32_e32 v3, 0, v3
	v_max_f32_e32 v4, 0, v4
	v_max_f32_e32 v5, 0, v5
	v_max_f32_e32 v6, 0, v6
	v_max_f32_e32 v7, 0, v7
	v_pk_mul_f32 v[0:1], v[0:1], v[0:1]
	v_pk_mul_f32 v[2:3], v[2:3], v[2:3]
	v_pk_mul_f32 v[4:5], v[4:5], v[4:5]
	v_pk_mul_f32 v[6:7], v[6:7], v[6:7]
	v_cvt_pk_bf16_f32 v4, v4, v5
	v_cvt_pk_bf16_f32 v5, v6, v7
	v_cvt_pk_bf16_f32 v6, v0, v1
	v_cvt_pk_bf16_f32 v7, v2, v3
	global_store_dwordx4 v250, v[4:7], s[100:101] offset:256
	s_add_u32 s100, s100, 0x40000
	s_addc_u32 s101, s101, 0
	s_cmp_lg_u64 s[82:83], 0
	s_cbranch_scc0 mk_p5_fin_nobar
	s_barrier
